# attn128 k-tile loop: next tile's 9 loads issued before the LDS-publish barrier (same cross-segment overlap as GEMM loops)
# baseline (speedup 1.0000x reference)
; #define MFMA(a, b, c) __builtin_amdgcn_mfma_f32_32x32x16_bf16((a), (b), (c), 0, 0, 0)
; template <int DQ, bool MASK>
; DI void attn_phase(const Params& p, unsigned char* smem, float cexp) {
;     ...
;     for (int kt = 0; kt < ntile_block; ++kt) {
;       __syncthreads();
;       {
;         constexpr int CPR = DQ / 8;
; #pragma unroll
;         for (int i = 0; i < DQ / 32; ++i) {
;           int c = tid + 256 * i;
;           int row = c / CPR, cc = c % CPR;
;           uint4 v = *(const uint4*)(Kb + ((size_t)bh * 2048 + kt * 64 + row) * DQ + cc * 8);
;           *(uint4*)(Ks + row * KST + cc * 8) = v;
;         }
; #pragma unroll
;         for (int i = 0; i < 4; ++i) {
;           int c = tid + 256 * i;
;           int d = c >> 3, cc = c & 7;
;           uint4 v = *(const uint4*)(Vt + (((size_t)bh * 32 + kt) * 128 + d) * 64 + cc * 8);
;           uint2* dp = (uint2*)(Vs + d * VST + cc * 8);
;           dp[0] = make_uint2(v.x, v.y);
;           dp[1] = make_uint2(v.z, v.w);
;         }
;       }
;       __syncthreads();
;       if (kt < my_nt) {
;         f32x16 sa[2];
; #pragma unroll
;         for (int u = 0; u < 2; ++u) {
; #pragma unroll
;           for (int i = 0; i < 16; ++i) sa[u][i] = 0.f;
; #pragma unroll
;           for (int s = 0; s < DQ / 16; ++s) {
;             bf16x8 a = *(const bf16x8*)(Ks + (32 * u + r) * KST + 16 * s + 8 * g);
;             sa[u] = MFMA(a, qf[s], sa[u]);
;           }
;         }
;         if (MASK) {
;           u64 mw = mask[tok * 32 + kt] >> (4 * g);
;           const u32 mlo = (u32)mw, mhi = (u32)(mw >> 32);
; #pragma unroll
;           for (int i = 0; i < 16; ++i) {
;             const u32 bit = 1u << ((i & 3) + 8 * (i >> 2));
;             if (!(mlo & bit)) sa[0][i] = -INFINITY;
;             if (!(mhi & bit)) sa[1][i] = -INFINITY;
;           }
;         }
.LBB0_1260:
	s_barrier
	v_cmp_lt_i32_e32 vcc, s10, v198
	s_waitcnt vmcnt(7)
	ds_write_b128 v187, v[200:203]
	s_waitcnt vmcnt(6)
	ds_write_b128 v188, v[204:207]
	s_waitcnt vmcnt(5)
	ds_write_b128 v189, v[208:211]
	s_waitcnt vmcnt(4)
	ds_write_b128 v190, v[212:215]
	s_waitcnt vmcnt(3)
	ds_write2_b64 v191, v[226:227], v[228:229] offset1:1
	s_waitcnt vmcnt(2)
	ds_write2_b64 v192, v[230:231], v[232:233] offset1:1
	s_waitcnt vmcnt(1)
	ds_write2_b64 v193, v[234:235], v[236:237] offset1:1
	s_waitcnt vmcnt(0)
	ds_write2_b64 v194, v[238:239], v[240:241] offset1:1
	v_lshl_add_u64 v[242:243], s[22:23], 0, v[184:185]
	global_load_dwordx2 v[244:245], v[242:243], off
	s_add_i32 s60, s10, 1
	s_cmp_eq_u32 s60, s25
	s_cselect_b64 s[72:73], s[68:69], s[64:65]
	s_cselect_b64 s[74:75], s[70:71], s[66:67]
	v_lshl_add_u64 v[246:247], s[72:73], 0, v[176:177]
	global_load_dwordx4 v[200:203], v[246:247], off
	v_lshl_add_u64 v[248:249], s[72:73], 0, v[178:179]
	global_load_dwordx4 v[204:207], v[248:249], off
	v_lshl_add_u64 v[246:247], s[72:73], 0, v[180:181]
	global_load_dwordx4 v[208:211], v[246:247], off
	v_lshl_add_u64 v[248:249], s[72:73], 0, v[182:183]
	global_load_dwordx4 v[212:215], v[248:249], off
	v_lshl_add_u64 v[246:247], s[74:75], 0, v[174:175]
	global_load_dwordx4 v[226:229], v[246:247], off
	v_lshl_add_u64 v[248:249], s[74:75], 0, v[172:173]
	global_load_dwordx4 v[230:233], v[248:249], off
	v_lshl_add_u64 v[246:247], s[74:75], 0, v[170:171]
	global_load_dwordx4 v[234:237], v[246:247], off
	v_lshl_add_u64 v[248:249], s[74:75], 0, v[168:169]
	global_load_dwordx4 v[238:241], v[248:249], off
	s_waitcnt lgkmcnt(0)
	s_barrier
	s_and_saveexec_b64 s[16:17], vcc
	s_cbranch_execz .LBB0_1259
	ds_read_b128 v[4:7], v195
	ds_read_b128 v[8:11], v195 offset:8704
	ds_read_b128 v[12:15], v195 offset:32
	ds_read_b128 v[250:253], v195 offset:8736
	s_waitcnt lgkmcnt(3)
	v_mfma_f32_32x32x16_bf16 v[80:95], v[4:7], v[112:115], 0
	ds_read_b128 v[4:7], v195 offset:64
	s_waitcnt lgkmcnt(3)
	v_mfma_f32_32x32x16_bf16 v[96:111], v[8:11], v[112:115], 0
	ds_read_b128 v[8:11], v195 offset:8768
	s_waitcnt lgkmcnt(3)
	v_mfma_f32_32x32x16_bf16 v[80:95], v[12:15], v[116:119], v[80:95]
	ds_read_b128 v[12:15], v195 offset:96
	s_waitcnt lgkmcnt(3)
	v_mfma_f32_32x32x16_bf16 v[96:111], v[250:253], v[116:119], v[96:111]
	ds_read_b128 v[250:253], v195 offset:8800
	s_waitcnt lgkmcnt(3)
	v_mfma_f32_32x32x16_bf16 v[80:95], v[4:7], v[120:123], v[80:95]
	ds_read_b128 v[4:7], v195 offset:128
	s_waitcnt lgkmcnt(3)
	v_mfma_f32_32x32x16_bf16 v[96:111], v[8:11], v[120:123], v[96:111]
	ds_read_b128 v[8:11], v195 offset:8832
	s_waitcnt lgkmcnt(3)
	v_mfma_f32_32x32x16_bf16 v[80:95], v[12:15], v[124:127], v[80:95]
	ds_read_b128 v[12:15], v195 offset:160
	s_waitcnt lgkmcnt(3)
	v_mfma_f32_32x32x16_bf16 v[96:111], v[250:253], v[124:127], v[96:111]
	ds_read_b128 v[250:253], v195 offset:8864
	s_waitcnt lgkmcnt(3)
	v_mfma_f32_32x32x16_bf16 v[80:95], v[4:7], v[128:131], v[80:95]
	ds_read_b128 v[4:7], v195 offset:192
	s_waitcnt lgkmcnt(3)
	v_mfma_f32_32x32x16_bf16 v[96:111], v[8:11], v[128:131], v[96:111]
	ds_read_b128 v[8:11], v195 offset:8896
	s_waitcnt lgkmcnt(3)
	v_mfma_f32_32x32x16_bf16 v[80:95], v[12:15], v[132:135], v[80:95]
	ds_read_b128 v[12:15], v195 offset:224
	s_waitcnt lgkmcnt(3)
	v_mfma_f32_32x32x16_bf16 v[96:111], v[250:253], v[132:135], v[96:111]
	ds_read_b128 v[250:253], v195 offset:8928
	s_waitcnt lgkmcnt(3)
	v_mfma_f32_32x32x16_bf16 v[80:95], v[4:7], v[136:139], v[80:95]
	s_waitcnt lgkmcnt(2)
	v_mfma_f32_32x32x16_bf16 v[96:111], v[8:11], v[136:139], v[96:111]
	s_waitcnt lgkmcnt(1)
	v_mfma_f32_32x32x16_bf16 v[80:95], v[12:15], v[140:143], v[80:95]
	s_waitcnt lgkmcnt(0)
	v_mfma_f32_32x32x16_bf16 v[96:111], v[250:253], v[140:143], v[96:111]
	s_waitcnt vmcnt(8)
	v_mov_b32_e32 v4, v244
	v_mov_b32_e32 v5, v245
	v_lshrrev_b32_e32 v3, v148, v4
	s_nop 7
	s_nop 1
	v_lshrrev_b64 v[12:13], v148, v[4:5]
	v_and_b32_e32 v3, 1, v3
	v_cmp_eq_u32_e32 vcc, 1, v3
	v_and_b32_e32 v3, 1, v13
	s_nop 0
	v_cndmask_b32_e32 v14, v197, v80, vcc
	v_cmp_eq_u32_e32 vcc, 1, v3
	v_and_b32_e32 v3, 2, v12
	s_nop 3
	v_cndmask_b32_e32 v10, v197, v96, vcc
	v_cmp_ne_u32_e32 vcc, 0, v3
	v_and_b32_e32 v3, 2, v13
	s_nop 0
	v_cndmask_b32_e32 v11, v197, v81, vcc
	v_cmp_ne_u32_e32 vcc, 0, v3
	v_and_b32_e32 v3, 4, v12
	s_nop 0
	v_cndmask_b32_e32 v15, v197, v97, vcc
	v_cmp_ne_u32_e32 vcc, 0, v3
	v_and_b32_e32 v3, 4, v13
	s_nop 0
	v_cndmask_b32_e32 v80, v197, v82, vcc
	v_cmp_ne_u32_e32 vcc, 0, v3
	v_and_b32_e32 v3, 8, v12
	s_nop 0
	v_cndmask_b32_e32 v96, v197, v98, vcc
	v_cmp_ne_u32_e32 vcc, 0, v3
	v_and_b32_e32 v3, 8, v13
	s_nop 0
	v_cndmask_b32_e32 v81, v197, v83, vcc
	v_cmp_ne_u32_e32 vcc, 0, v3
	v_and_b32_e32 v3, 0x100, v12
	s_nop 0
	v_cndmask_b32_e32 v97, v197, v99, vcc
	v_cmp_ne_u32_e32 vcc, 0, v3
	v_and_b32_e32 v3, 0x100, v13
	s_nop 0
	v_cndmask_b32_e32 v82, v197, v84, vcc
	v_cmp_ne_u32_e32 vcc, 0, v3
	v_and_b32_e32 v3, 0x200, v12
	s_nop 0
	v_cndmask_b32_e32 v98, v197, v100, vcc
	v_cmp_ne_u32_e32 vcc, 0, v3
	v_and_b32_e32 v3, 0x200, v13
	s_nop 0
	v_cndmask_b32_e32 v83, v197, v85, vcc
	v_cmp_ne_u32_e32 vcc, 0, v3
	v_and_b32_e32 v3, 0x400, v12
	s_nop 0
	v_cndmask_b32_e32 v99, v197, v101, vcc
	v_cmp_ne_u32_e32 vcc, 0, v3
	v_and_b32_e32 v3, 0x400, v13
	s_nop 0
	v_cndmask_b32_e32 v84, v197, v86, vcc
	v_cmp_ne_u32_e32 vcc, 0, v3
	v_and_b32_e32 v3, 0x800, v12
	s_nop 0
	v_cndmask_b32_e32 v100, v197, v102, vcc
	v_cmp_ne_u32_e32 vcc, 0, v3
	v_and_b32_e32 v3, 0x800, v13
	s_nop 0
	v_cndmask_b32_e32 v85, v197, v87, vcc
	v_cmp_ne_u32_e32 vcc, 0, v3
	v_and_b32_e32 v3, 0x10000, v12
	s_nop 0
	v_cndmask_b32_e32 v101, v197, v103, vcc
	v_cmp_ne_u32_e32 vcc, 0, v3
; #define MFMA(a, b, c) __builtin_amdgcn_mfma_f32_32x32x16_bf16((a), (b), (c), 0, 0, 0)
; template <int DQ, bool MASK>
; DI void attn_phase(const Params& p, unsigned char* smem, float cexp) {
;     ...
;         if (MASK) {
;           u64 mw = mask[tok * 32 + kt] >> (4 * g);
;           const u32 mlo = (u32)mw, mhi = (u32)(mw >> 32);
; #pragma unroll
;           for (int i = 0; i < 16; ++i) {
;             const u32 bit = 1u << ((i & 3) + 8 * (i >> 2));
;             if (!(mlo & bit)) sa[0][i] = -INFINITY;
;             if (!(mhi & bit)) sa[1][i] = -INFINITY;
;           }
;         }
;         float mx = -INFINITY;
; #pragma unroll
;         for (int u = 0; u < 2; ++u)
; #pragma unroll
;           for (int i = 0; i < 16; ++i) mx = fmaxf(mx, sa[u][i]);
;         mx = fmaxf(mx, __shfl_xor(mx, 32));
;         float mnew = fmaxf(m, mx);
;         float muse = (mnew == -INFINITY) ? 0.f : mnew;
;         float alpha = __builtin_amdgcn_exp2f((m - muse) * cexp);
;         m = mnew;
;         float ps = 0.f;
; #pragma unroll
;         for (int u = 0; u < 2; ++u)
; #pragma unroll
;           for (int i = 0; i < 16; ++i) {
;             float pv = __builtin_amdgcn_exp2f((sa[u][i] - muse) * cexp);
;             ps += pv;
;             sa[u][i] = pv;
;           }
;         l = l * alpha + ps;
; #pragma unroll
;         for (int j = 0; j < 4; ++j)
; #pragma unroll
;           for (int i = 0; i < 16; ++i) o[j][i] *= alpha;
; #pragma unroll
;         for (int u = 0; u < 2; ++u)
; #pragma unroll
;           for (int s2 = 0; s2 < 2; ++s2) {
;             uint4 pp;
;             pp.x = pack2(sa[u][8 * s2 + 0], sa[u][8 * s2 + 1]);
;             pp.y = pack2(sa[u][8 * s2 + 2], sa[u][8 * s2 + 3]);
;             pp.z = pack2(sa[u][8 * s2 + 4], sa[u][8 * s2 + 5]);
;             pp.w = pack2(sa[u][8 * s2 + 6], sa[u][8 * s2 + 7]);
;             bf16x8 pf = __builtin_bit_cast(bf16x8, pp);
; #pragma unroll
;             for (int dt = 0; dt < 4; ++dt) {
;               const bf16* vp = Vs + (32 * dt + r) * VST + 32 * u + 16 * s2 + 4 * g;
;               s16x4 lo = *(const s16x4*)vp;
;               s16x4 hi = *(const s16x4*)(vp + 8);
;               bf16x8 vf = __builtin_shufflevector(lo, hi, 0, 1, 2, 3, 4, 5, 6, 7);
;               o[dt] = MFMA(vf, pf, o[dt]);
	v_and_b32_e32 v3, 0x10000, v13
	s_nop 0
	v_cndmask_b32_e32 v86, v197, v88, vcc
	v_cmp_ne_u32_e32 vcc, 0, v3
	v_and_b32_e32 v3, 0x20000, v12
	s_nop 0
	v_cndmask_b32_e32 v88, v197, v104, vcc
	v_cmp_ne_u32_e32 vcc, 0, v3
	v_and_b32_e32 v3, 0x20000, v13
	s_nop 0
	v_cndmask_b32_e32 v87, v197, v89, vcc
	v_cmp_ne_u32_e32 vcc, 0, v3
	v_and_b32_e32 v3, 0x40000, v12
	s_nop 0
	v_cndmask_b32_e32 v89, v197, v105, vcc
	v_cmp_ne_u32_e32 vcc, 0, v3
	v_and_b32_e32 v3, 0x40000, v13
	s_nop 0
	v_cndmask_b32_e32 v90, v197, v90, vcc
	v_cmp_ne_u32_e32 vcc, 0, v3
	v_and_b32_e32 v3, 0x80000, v12
	s_nop 0
	v_cndmask_b32_e32 v8, v197, v106, vcc
	v_cmp_ne_u32_e32 vcc, 0, v3
	v_and_b32_e32 v3, 0x80000, v13
	s_nop 0
	v_cndmask_b32_e32 v91, v197, v91, vcc
	v_cmp_ne_u32_e32 vcc, 0, v3
	v_and_b32_e32 v3, 0x1000000, v12
	s_nop 0
	v_cndmask_b32_e32 v9, v197, v107, vcc
	v_cmp_ne_u32_e32 vcc, 0, v3
	v_and_b32_e32 v3, 0x1000000, v13
	s_nop 0
	v_cndmask_b32_e32 v92, v197, v92, vcc
	v_cmp_ne_u32_e32 vcc, 0, v3
	v_and_b32_e32 v3, 0x2000000, v12
	s_nop 0
	v_cndmask_b32_e32 v6, v197, v108, vcc
	v_cmp_ne_u32_e32 vcc, 0, v3
	v_and_b32_e32 v3, 0x2000000, v13
	s_nop 0
	v_cndmask_b32_e32 v93, v197, v93, vcc
	v_cmp_ne_u32_e32 vcc, 0, v3
	v_and_b32_e32 v3, 0x4000000, v12
	s_nop 0
	v_cndmask_b32_e32 v7, v197, v109, vcc
	v_cmp_ne_u32_e32 vcc, 0, v3
	v_and_b32_e32 v3, 0x4000000, v13
	s_nop 0
	v_cndmask_b32_e32 v94, v197, v94, vcc
	v_cmp_ne_u32_e32 vcc, 0, v3
	v_and_b32_e32 v3, 0x8000000, v12
	s_nop 0
	v_cndmask_b32_e32 v4, v197, v110, vcc
	v_cmp_ne_u32_e32 vcc, 0, v3
	v_and_b32_e32 v3, 0x8000000, v13
	v_add_u32_e32 v110, 0x4000, v196
	v_cndmask_b32_e32 v12, v197, v95, vcc
	v_cmp_ne_u32_e32 vcc, 0, v3
	v_max3_f32 v3, v14, s5, v11
	v_max3_f32 v3, v3, v80, v81
	v_max3_f32 v3, v3, v82, v83
	v_max3_f32 v3, v3, v84, v85
	v_max3_f32 v3, v3, v86, v87
	v_max3_f32 v3, v3, v90, v91
	v_max3_f32 v3, v3, v92, v93
	v_max3_f32 v3, v3, v94, v12
	v_max3_f32 v3, v3, v10, v15
	v_max3_f32 v3, v3, v96, v97
	v_max3_f32 v3, v3, v98, v99
	v_max3_f32 v3, v3, v100, v101
	v_max3_f32 v3, v3, v88, v89
	v_max3_f32 v3, v3, v8, v9
	v_cndmask_b32_e32 v5, v197, v111, vcc
	v_max3_f32 v3, v3, v6, v7
	v_max3_f32 v3, v3, v4, v5
	v_mov_b32_e32 v13, v3
	s_nop 1
	v_permlane32_swap_b32_e32 v3, v13
	v_add_u32_e32 v111, 0x7000, v196
	s_waitcnt lgkmcnt(0)
	v_max3_f32 v3, v2, v3, v13
	v_cmp_neq_f32_e32 vcc, s5, v3
	s_nop 1
	v_cndmask_b32_e32 v95, 0, v3, vcc
	v_sub_f32_e32 v11, v11, v95
	v_sub_f32_e32 v13, v14, v95
	v_mul_f32_e32 v11, 0x3e0293ee, v11
	v_mul_f32_e32 v13, 0x3e0293ee, v13
	v_exp_f32_e32 v102, v11
	v_sub_f32_e32 v11, v80, v95
	v_exp_f32_e32 v14, v13
	v_mul_f32_e32 v11, 0x3e0293ee, v11
	v_exp_f32_e32 v103, v11
	v_sub_f32_e32 v11, v81, v95
	v_mul_f32_e32 v11, 0x3e0293ee, v11
	v_exp_f32_e32 v81, v11
	v_sub_f32_e32 v11, v82, v95
	v_add_f32_e32 v13, 0, v14
	v_mul_f32_e32 v11, 0x3e0293ee, v11
	v_exp_f32_e32 v82, v11
	v_add_f32_e32 v11, v102, v13
	v_sub_f32_e32 v13, v83, v95
	v_mul_f32_e32 v13, 0x3e0293ee, v13
	v_exp_f32_e32 v83, v13
	v_sub_f32_e32 v13, v84, v95
	v_mul_f32_e32 v13, 0x3e0293ee, v13
	v_exp_f32_e32 v84, v13
	v_sub_f32_e32 v13, v85, v95
	v_mul_f32_e32 v13, 0x3e0293ee, v13
	v_exp_f32_e32 v85, v13
	v_sub_f32_e32 v13, v86, v95
	v_mul_f32_e32 v13, 0x3e0293ee, v13
	v_exp_f32_e32 v104, v13
	v_sub_f32_e32 v13, v87, v95
	v_mul_f32_e32 v13, 0x3e0293ee, v13
	v_add_f32_e32 v11, v103, v11
	v_exp_f32_e32 v105, v13
	v_sub_f32_e32 v13, v90, v95
	v_add_f32_e32 v11, v81, v11
	v_mul_f32_e32 v13, 0x3e0293ee, v13
	v_add_f32_e32 v11, v82, v11
	v_exp_f32_e32 v90, v13
	v_sub_f32_e32 v13, v91, v95
	v_add_f32_e32 v11, v83, v11
	v_mul_f32_e32 v13, 0x3e0293ee, v13
	v_add_f32_e32 v11, v84, v11
	v_exp_f32_e32 v91, v13
	v_sub_f32_e32 v13, v92, v95
	v_add_f32_e32 v11, v85, v11
	v_mul_f32_e32 v13, 0x3e0293ee, v13
	v_add_f32_e32 v11, v104, v11
	v_exp_f32_e32 v92, v13
	v_add_f32_e32 v11, v105, v11
	v_add_f32_e32 v11, v90, v11
	v_add_f32_e32 v11, v91, v11
	v_add_f32_e32 v106, v92, v11
	v_sub_f32_e32 v11, v93, v95
	v_mul_f32_e32 v11, 0x3e0293ee, v11
	v_exp_f32_e32 v93, v11
	v_sub_f32_e32 v11, v94, v95
	v_sub_f32_e32 v10, v10, v95
	v_mul_f32_e32 v11, 0x3e0293ee, v11
	v_mul_f32_e32 v10, 0x3e0293ee, v10
	v_exp_f32_e32 v94, v11
	v_sub_f32_e32 v11, v12, v95
	v_exp_f32_e32 v108, v10
	v_sub_f32_e32 v10, v15, v95
	v_mul_f32_e32 v11, 0x3e0293ee, v11
	v_mul_f32_e32 v10, 0x3e0293ee, v10
	v_exp_f32_e32 v107, v11
	v_exp_f32_e32 v109, v10
	ds_read2_b64 v[10:13], v110 offset0:128 offset1:130
	v_sub_f32_e32 v2, v2, v95
	v_mul_f32_e32 v2, 0x3e0293ee, v2
	v_exp_f32_e32 v2, v2
	v_cvt_pk_bf16_f32 v80, v14, v102
	v_add_u32_e32 v102, 0x5000, v196
	v_cvt_pk_bf16_f32 v81, v103, v81
	v_pk_mul_f32 v[78:79], v[78:79], v[2:3] op_sel_hi:[1,0]
	v_pk_mul_f32 v[76:77], v[76:77], v[2:3] op_sel_hi:[1,0]
	v_pk_mul_f32 v[74:75], v[74:75], v[2:3] op_sel_hi:[1,0]
	v_pk_mul_f32 v[72:73], v[72:73], v[2:3] op_sel_hi:[1,0]
	v_pk_mul_f32 v[70:71], v[70:71], v[2:3] op_sel_hi:[1,0]
	v_pk_mul_f32 v[68:69], v[68:69], v[2:3] op_sel_hi:[1,0]
	v_pk_mul_f32 v[66:67], v[66:67], v[2:3] op_sel_hi:[1,0]
	v_pk_mul_f32 v[64:65], v[64:65], v[2:3] op_sel_hi:[1,0]
	v_cvt_pk_bf16_f32 v82, v82, v83
	v_cvt_pk_bf16_f32 v83, v84, v85
	ds_read2_b64 v[84:87], v102 offset0:160 offset1:162
	v_add_u32_e32 v103, 0x6000, v196
	s_waitcnt lgkmcnt(1)
; #define MFMA(a, b, c) __builtin_amdgcn_mfma_f32_32x32x16_bf16((a), (b), (c), 0, 0, 0)
; template <int DQ, bool MASK>
; DI void attn_phase(const Params& p, unsigned char* smem, float cexp) {
;     ...
;         float alpha = __builtin_amdgcn_exp2f((m - muse) * cexp);
;         m = mnew;
;         float ps = 0.f;
; #pragma unroll
;         for (int u = 0; u < 2; ++u)
; #pragma unroll
;           for (int i = 0; i < 16; ++i) {
;             float pv = __builtin_amdgcn_exp2f((sa[u][i] - muse) * cexp);
;             ps += pv;
;             sa[u][i] = pv;
;           }
;         l = l * alpha + ps;
; #pragma unroll
;         for (int j = 0; j < 4; ++j)
; #pragma unroll
;           for (int i = 0; i < 16; ++i) o[j][i] *= alpha;
; #pragma unroll
;         for (int u = 0; u < 2; ++u)
; #pragma unroll
;           for (int s2 = 0; s2 < 2; ++s2) {
;             uint4 pp;
;             pp.x = pack2(sa[u][8 * s2 + 0], sa[u][8 * s2 + 1]);
;             pp.y = pack2(sa[u][8 * s2 + 2], sa[u][8 * s2 + 3]);
;             pp.z = pack2(sa[u][8 * s2 + 4], sa[u][8 * s2 + 5]);
;             pp.w = pack2(sa[u][8 * s2 + 6], sa[u][8 * s2 + 7]);
;             bf16x8 pf = __builtin_bit_cast(bf16x8, pp);
; #pragma unroll
;             for (int dt = 0; dt < 4; ++dt) {
;               const bf16* vp = Vs + (32 * dt + r) * VST + 32 * u + 16 * s2 + 4 * g;
;               s16x4 lo = *(const s16x4*)vp;
;               s16x4 hi = *(const s16x4*)(vp + 8);
;               bf16x8 vf = __builtin_shufflevector(lo, hi, 0, 1, 2, 3, 4, 5, 6, 7);
;               o[dt] = MFMA(vf, pf, o[dt]);
;             }
;           }
	v_mfma_f32_32x32x16_bf16 v[64:79], v[10:13], v[80:83], v[64:79]
	ds_read2_b64 v[10:13], v103 offset0:192 offset1:194
	v_mul_f32_e64 v62, v62, v2
	v_mul_f32_e64 v63, v63, v2
	v_mul_f32_e64 v60, v60, v2
	v_mul_f32_e64 v61, v61, v2
	v_pk_mul_f32 v[58:59], v[58:59], v[2:3] op_sel_hi:[1,0]
	v_pk_mul_f32 v[56:57], v[56:57], v[2:3] op_sel_hi:[1,0]
	v_pk_mul_f32 v[54:55], v[54:55], v[2:3] op_sel_hi:[1,0]
	v_pk_mul_f32 v[52:53], v[52:53], v[2:3] op_sel_hi:[1,0]
	v_pk_mul_f32 v[50:51], v[50:51], v[2:3] op_sel_hi:[1,0]
	v_pk_mul_f32 v[48:49], v[48:49], v[2:3] op_sel_hi:[1,0]
	v_pk_mul_f32 v[46:47], v[46:47], v[2:3] op_sel_hi:[1,0]
	v_pk_mul_f32 v[44:45], v[44:45], v[2:3] op_sel_hi:[1,0]
	v_pk_mul_f32 v[42:43], v[42:43], v[2:3] op_sel_hi:[1,0]
	v_pk_mul_f32 v[40:41], v[40:41], v[2:3] op_sel_hi:[1,0]
	v_pk_mul_f32 v[38:39], v[38:39], v[2:3] op_sel_hi:[1,0]
	s_waitcnt lgkmcnt(1)
	v_mfma_f32_32x32x16_bf16 v[48:63], v[84:87], v[80:83], v[48:63]
	v_mul_f32_e64 v36, v36, v2
	v_mul_f32_e64 v37, v37, v2
	v_mul_f32_e64 v34, v34, v2
	v_mul_f32_e64 v35, v35, v2
	v_mul_f32_e64 v32, v32, v2
	v_mul_f32_e64 v33, v33, v2
	ds_read2_b64 v[84:87], v111 offset0:224 offset1:226
	v_pk_mul_f32 v[30:31], v[30:31], v[2:3] op_sel_hi:[1,0]
	v_pk_mul_f32 v[28:29], v[28:29], v[2:3] op_sel_hi:[1,0]
	v_pk_mul_f32 v[26:27], v[26:27], v[2:3] op_sel_hi:[1,0]
	s_waitcnt lgkmcnt(1)
	v_mfma_f32_32x32x16_bf16 v[32:47], v[10:13], v[80:83], v[32:47]
	ds_read2_b64 v[10:13], v110 offset0:132 offset1:134
	v_mul_f32_e64 v24, v24, v2
	v_mul_f32_e64 v25, v25, v2
	v_mul_f32_e64 v22, v22, v2
	v_mul_f32_e64 v23, v23, v2
	v_pk_mul_f32 v[20:21], v[20:21], v[2:3] op_sel_hi:[1,0]
	v_pk_mul_f32 v[18:19], v[18:19], v[2:3] op_sel_hi:[1,0]
	v_pk_mul_f32 v[16:17], v[16:17], v[2:3] op_sel_hi:[1,0]
	v_sub_f32_e32 v14, v96, v95
	v_mul_f32_e32 v14, 0x3e0293ee, v14
	s_waitcnt lgkmcnt(1)
	v_mfma_f32_32x32x16_bf16 v[16:31], v[84:87], v[80:83], v[16:31]
	v_cvt_pk_bf16_f32 v80, v104, v105
	v_cvt_pk_bf16_f32 v81, v90, v91
	v_cvt_pk_bf16_f32 v82, v92, v93
	v_cvt_pk_bf16_f32 v83, v94, v107
	ds_read2_b64 v[84:87], v102 offset0:164 offset1:166
	v_exp_f32_e32 v90, v14
	v_sub_f32_e32 v8, v8, v95
	s_waitcnt lgkmcnt(1)
	v_mfma_f32_32x32x16_bf16 v[64:79], v[10:13], v[80:83], v[64:79]
	v_sub_f32_e32 v10, v97, v95
	v_mul_f32_e32 v10, 0x3e0293ee, v10
	v_exp_f32_e32 v91, v10
	v_sub_f32_e32 v10, v98, v95
	v_mul_f32_e32 v14, 0x3e0293ee, v10
	ds_read2_b64 v[10:13], v103 offset0:196 offset1:198
	v_exp_f32_e32 v92, v14
	s_waitcnt lgkmcnt(1)
	v_mfma_f32_32x32x16_bf16 v[48:63], v[84:87], v[80:83], v[48:63]
	v_sub_f32_e32 v14, v99, v95
	ds_read2_b64 v[84:87], v111 offset0:228 offset1:230
	v_mul_f32_e32 v14, 0x3e0293ee, v14
	v_exp_f32_e32 v96, v14
	v_sub_f32_e32 v14, v100, v95
	v_mul_f32_e32 v14, 0x3e0293ee, v14
	v_exp_f32_e32 v97, v14
	s_waitcnt lgkmcnt(1)
	v_mfma_f32_32x32x16_bf16 v[32:47], v[10:13], v[80:83], v[32:47]
	v_sub_f32_e32 v10, v101, v95
	v_mul_f32_e32 v10, 0x3e0293ee, v10
	v_exp_f32_e32 v98, v10
	v_sub_f32_e32 v10, v88, v95
	v_mul_f32_e32 v14, 0x3e0293ee, v10
	ds_read2_b64 v[10:13], v110 offset0:136 offset1:138
	v_exp_f32_e32 v88, v14
	s_waitcnt lgkmcnt(1)
	v_mfma_f32_32x32x16_bf16 v[16:31], v[84:87], v[80:83], v[16:31]
	ds_read2_b64 v[84:87], v102 offset0:168 offset1:170
	v_sub_f32_e32 v14, v89, v95
	v_cvt_pk_bf16_f32 v80, v108, v109
	v_cvt_pk_bf16_f32 v81, v90, v91
	v_cvt_pk_bf16_f32 v82, v92, v96
	v_cvt_pk_bf16_f32 v83, v97, v98
	v_mul_f32_e32 v8, 0x3e0293ee, v8
	v_exp_f32_e32 v99, v8
	s_waitcnt lgkmcnt(1)
	v_mfma_f32_32x32x16_bf16 v[64:79], v[10:13], v[80:83], v[64:79]
	v_mul_f32_e32 v10, 0x3e0293ee, v14
	v_exp_f32_e32 v89, v10
	v_sub_f32_e32 v12, v9, v95
	ds_read2_b64 v[8:11], v103 offset0:200 offset1:202
	v_mul_f32_e32 v12, 0x3e0293ee, v12
	v_sub_f32_e32 v6, v6, v95
	v_mul_f32_e32 v6, 0x3e0293ee, v6
	s_waitcnt lgkmcnt(1)
	v_mfma_f32_32x32x16_bf16 v[48:63], v[84:87], v[80:83], v[48:63]
	v_exp_f32_e32 v84, v12
	ds_read2_b64 v[12:15], v111 offset0:232 offset1:234
	v_exp_f32_e32 v85, v6
	v_sub_f32_e32 v6, v7, v95
	v_sub_f32_e32 v4, v4, v95
	v_mul_f32_e32 v6, 0x3e0293ee, v6
	v_mul_f32_e32 v4, 0x3e0293ee, v4
	s_waitcnt lgkmcnt(1)
	v_mfma_f32_32x32x16_bf16 v[32:47], v[8:11], v[80:83], v[32:47]
	v_exp_f32_e32 v86, v6
	v_exp_f32_e32 v87, v4
	v_sub_f32_e32 v8, v5, v95
	ds_read2_b64 v[4:7], v110 offset0:140 offset1:142
	v_mul_f32_e32 v8, 0x3e0293ee, v8
	v_cvt_pk_bf16_f32 v9, v99, v84
	v_cvt_pk_bf16_f32 v10, v85, v86
	s_waitcnt lgkmcnt(1)
	v_mfma_f32_32x32x16_bf16 v[16:31], v[12:15], v[80:83], v[16:31]
	v_exp_f32_e32 v80, v8
	ds_read2_b64 v[12:15], v102 offset0:172 offset1:174
	v_cvt_pk_bf16_f32 v8, v88, v89
	v_cvt_pk_bf16_f32 v11, v87, v80
	s_waitcnt lgkmcnt(1)
	s_nop 0
	v_mfma_f32_32x32x16_bf16 v[64:79], v[4:7], v[8:11], v[64:79]
	v_add_f32_e32 v4, v93, v106
	v_add_f32_e32 v4, v94, v4
	v_add_f32_e32 v4, v107, v4
	v_add_f32_e32 v4, v108, v4
	v_add_f32_e32 v4, v109, v4
	v_add_f32_e32 v81, v90, v4
	ds_read2_b64 v[4:7], v103 offset0:204 offset1:206
	s_waitcnt lgkmcnt(1)
	v_mfma_f32_32x32x16_bf16 v[48:63], v[12:15], v[8:11], v[48:63]
	v_add_f32_e32 v12, v91, v81
	v_add_f32_e32 v12, v92, v12
	v_add_f32_e32 v12, v96, v12
	v_add_f32_e32 v12, v97, v12
	v_add_f32_e32 v12, v98, v12
	v_add_f32_e32 v81, v88, v12
	ds_read2_b64 v[12:15], v111 offset0:236 offset1:238
	s_waitcnt lgkmcnt(1)
	v_mfma_f32_32x32x16_bf16 v[32:47], v[4:7], v[8:11], v[32:47]
	v_add_f32_e32 v4, v89, v81
	v_add_f32_e32 v4, v99, v4
	v_add_f32_e32 v4, v84, v4
	v_add_f32_e32 v4, v85, v4
	v_add_f32_e32 v4, v86, v4
	v_add_f32_e32 v4, v87, v4
	v_add_f32_e32 v4, v80, v4
	s_waitcnt lgkmcnt(0)
	v_mfma_f32_32x32x16_bf16 v[16:31], v[12:15], v[8:11], v[16:31]
	v_fmac_f32_e32 v4, v1, v2
	v_mov_b32_e32 v1, v4
	v_mov_b32_e32 v2, v3
	s_branch .LBB0_1259
